# NSA tile fast path: exp/cvt/PV pipelined per 8-key chunk (PV MFMAs of chunk c beside exps of chunk c+1), same sum and MFMA order
# speedup vs baseline: 1.0228x; 1.0086x over previous
; #define LAS __attribute__((address_space(3)))
; DI float fexp2(float x) { return __builtin_amdgcn_exp2f(x); }
; DI f32x16 mfma32(bf16x8 a, bf16x8 b, f32x16 c) { return __builtin_amdgcn_mfma_f32_32x32x16_bf16(a, b, c, 0, 0, 0); }
; DI void pv_sub(const LAS unsigned char* vt, int vstride, int koff_bytes, const f32x16& p, f32x16 (&o)[2], int r, int hh) {
;     const bf16x8 pf0 = pack8<0>(p), pf1 = pack8<1>(p);
; #pragma unroll
;     for (int st = 0; st < 2; ++st) {
;         u32x2 lo[2], hi[2];
; #pragma unroll
;         for (int u = 0; u < 2; ++u) {
;             const LAS unsigned char* a = vt + (32 * u + r) * vstride + koff_bytes + 32 * st + 8 * hh;
;             lo[u] = *(const LAS u32x2*)a; hi[u] = *(const LAS u32x2*)(a + 16);
;         }
;         __builtin_amdgcn_sched_barrier(0);
; #pragma unroll
;         for (int u = 0; u < 2; ++u) { u32x4 v; v.x = lo[u].x; v.y = lo[u].y; v.z = hi[u].x; v.w = hi[u].y; o[u] = mfma32(__builtin_bit_cast(bf16x8, v), st ? pf1 : pf0, o[u]); }
;     }
; }
; DI void softmax_lazy(f32x16 (&s)[2], float& m, float& l, f32x16 (&o)[2], int hh) {
;     ...
;     float sum = 0.f;
; #pragma unroll
;     for (int t = 0; t < 2; ++t)
; #pragma unroll
;         for (int i = 0; i < 16; ++i) { s[t][i] = fexp2(s[t][i]); sum += s[t][i]; }
;     sum += __shfl_xor(sum, 32);
;     l += sum;
.LBB0_2419:
	v_add3_u32 v0, s0, v211, v242
	v_add_u32_e32 v2, 0xa800, v0
	v_add_u32_e32 v0, 0xb800, v0
	ds_read2_b64 v[56:59], v2 offset0:192 offset1:194
	ds_read2_b64 v[60:63], v0 offset0:224 offset1:226
	v_exp_f32_e32 v160, v160
	v_exp_f32_e32 v161, v161
	v_exp_f32_e32 v162, v162
	v_exp_f32_e32 v163, v163
	v_exp_f32_e32 v164, v164
	v_exp_f32_e32 v165, v165
	v_exp_f32_e32 v166, v166
	v_exp_f32_e32 v167, v167
	v_add_f32_e32 v3, v161, v160
	v_add_f32_e32 v3, v162, v3
	v_add_f32_e32 v3, v163, v3
	v_add_f32_e32 v3, v164, v3
	v_add_f32_e32 v3, v165, v3
	v_add_f32_e32 v3, v166, v3
	v_add_f32_e32 v3, v167, v3
	v_cvt_pk_bf16_f32 v8, v160, v161
	v_cvt_pk_bf16_f32 v9, v162, v163
	v_cvt_pk_bf16_f32 v10, v164, v165
	v_cvt_pk_bf16_f32 v11, v166, v167
	v_exp_f32_e32 v168, v168
	v_exp_f32_e32 v169, v169
	v_exp_f32_e32 v170, v170
	v_exp_f32_e32 v171, v171
	s_waitcnt lgkmcnt(0)
	v_mfma_f32_32x32x16_bf16 v[128:143], v[56:59], v[8:11], v[128:143]
	v_exp_f32_e32 v172, v172
	v_exp_f32_e32 v173, v173
	v_exp_f32_e32 v174, v174
	v_exp_f32_e32 v175, v175
	v_mfma_f32_32x32x16_bf16 v[112:127], v[60:63], v[8:11], v[112:127]
	ds_read2_b64 v[64:67], v2 offset0:196 offset1:198
	ds_read2_b64 v[68:71], v0 offset0:228 offset1:230
	v_add_f32_e32 v3, v168, v3
	v_add_f32_e32 v3, v169, v3
	v_add_f32_e32 v3, v170, v3
	v_add_f32_e32 v3, v171, v3
	v_add_f32_e32 v3, v172, v3
	v_add_f32_e32 v3, v173, v3
	v_add_f32_e32 v3, v174, v3
	v_add_f32_e32 v3, v175, v3
	v_cvt_pk_bf16_f32 v12, v168, v169
	v_cvt_pk_bf16_f32 v13, v170, v171
	v_cvt_pk_bf16_f32 v14, v172, v173
	v_cvt_pk_bf16_f32 v15, v174, v175
	v_exp_f32_e32 v144, v144
	v_exp_f32_e32 v145, v145
	v_exp_f32_e32 v146, v146
	v_exp_f32_e32 v147, v147
	s_waitcnt lgkmcnt(0)
	v_mfma_f32_32x32x16_bf16 v[128:143], v[64:67], v[12:15], v[128:143]
	v_exp_f32_e32 v148, v148
	v_exp_f32_e32 v149, v149
	v_exp_f32_e32 v150, v150
	v_exp_f32_e32 v151, v151
	v_mfma_f32_32x32x16_bf16 v[112:127], v[68:71], v[12:15], v[112:127]
	ds_read2_b64 v[72:75], v2 offset0:200 offset1:202
	ds_read2_b64 v[76:79], v0 offset0:232 offset1:234
	v_add_f32_e32 v3, v144, v3
	v_add_f32_e32 v3, v145, v3
	v_add_f32_e32 v3, v146, v3
	v_add_f32_e32 v3, v147, v3
	v_add_f32_e32 v3, v148, v3
	v_add_f32_e32 v3, v149, v3
	v_add_f32_e32 v3, v150, v3
	v_add_f32_e32 v3, v151, v3
	v_cvt_pk_bf16_f32 v16, v144, v145
	v_cvt_pk_bf16_f32 v17, v146, v147
	v_cvt_pk_bf16_f32 v18, v148, v149
	v_cvt_pk_bf16_f32 v19, v150, v151
	v_exp_f32_e32 v152, v152
	v_exp_f32_e32 v153, v153
	v_exp_f32_e32 v154, v154
	v_exp_f32_e32 v155, v155
	s_waitcnt lgkmcnt(0)
	v_mfma_f32_32x32x16_bf16 v[128:143], v[72:75], v[16:19], v[128:143]
	v_exp_f32_e32 v156, v156
	v_exp_f32_e32 v157, v157
	v_exp_f32_e32 v158, v158
	v_exp_f32_e32 v159, v159
	v_mfma_f32_32x32x16_bf16 v[112:127], v[76:79], v[16:19], v[112:127]
	ds_read2_b64 v[144:147], v2 offset0:204 offset1:206
	ds_read2_b64 v[148:151], v0 offset0:236 offset1:238
	v_add_f32_e32 v3, v152, v3
	v_add_f32_e32 v3, v153, v3
	v_add_f32_e32 v3, v154, v3
	v_add_f32_e32 v3, v155, v3
	v_add_f32_e32 v3, v156, v3
	v_add_f32_e32 v3, v157, v3
	v_add_f32_e32 v3, v158, v3
	v_add_f32_e32 v3, v159, v3
	v_mov_b32_e32 v7, v3
	v_cvt_pk_bf16_f32 v52, v152, v153
	v_cvt_pk_bf16_f32 v53, v154, v155
	v_cvt_pk_bf16_f32 v54, v156, v157
	v_cvt_pk_bf16_f32 v55, v158, v159
	v_permlane32_swap_b32_e32 v7, v3
	v_add_f32_e32 v3, v3, v7
	v_add_f32_e32 v245, v245, v3
	s_waitcnt lgkmcnt(0)
	v_mfma_f32_32x32x16_bf16 v[128:143], v[144:147], v[52:55], v[128:143]
	v_mfma_f32_32x32x16_bf16 v[112:127], v[148:151], v[52:55], v[112:127]
